# NSA window and selected loops: LDS K/V fragment reads bursted into free VGPRs with counted lgkmcnt (V reads overlap the softmax); selected-loop accumulator exit copies hoisted to the exit edge
# speedup vs baseline: 1.0120x; 1.0040x over previous
; #define NEG_INF (-__builtin_inff())
; DI float xhalf_max(float v) { const auto r = __builtin_amdgcn_permlane32_swap(__float_as_uint(v), __float_as_uint(v), false, false); return fmaxf(__uint_as_float(r[0]), __uint_as_float(r[1])); }
; DI float fexp2(float x) { return __builtin_amdgcn_exp2f(x); }
; DI f32x16 mfma32(bf16x8 a, bf16x8 b, f32x16 c) { return __builtin_amdgcn_mfma_f32_32x32x16_bf16(a, b, c, 0, 0, 0); }
; #define LAS __attribute__((address_space(3)))
; DI bf16x8 pack8(const float* p) { u32x4 o; o.x = pk2h(p[0], p[1]); o.y = pk2h(p[2], p[3]); o.z = pk2h(p[4], p[5]); o.w = pk2h(p[6], p[7]); return __builtin_bit_cast(bf16x8, o); }
; DI void pv_tile_lds(f32x16 (&o)[4], const bf16x8 (&pf)[2], const LAS unsigned char* stv, const LaneKV& L) {
; #pragma unroll
;   for (int vt = 0; vt < 4; ++vt) {
; #pragma unroll
;     for (int s2 = 0; s2 < 2; ++s2) {
;       const s16x4 lo = *(const LAS s16x4*)(stv + vt * 2048 + L.vrow + L.vo[2 * s2]), hi = *(const LAS s16x4*)(stv + vt * 2048 + L.vrow + L.vo[2 * s2 + 1]);
;       const bf16x8 a = __builtin_shufflevector(lo, hi, 0, 1, 2, 3, 4, 5, 6, 7);
;       o[vt] = mfma32(a, pf[s2], o[vt]);
;     }
;   }
; }
; DI void softmax_step_lds(AttnState& st, float (&sc)[16], const LAS unsigned char* stv, const LaneKV& L) {
;   float mx = st.m;
; #pragma unroll
;   for (int i = 0; i < 16; ++i) mx = fmaxf(mx, sc[i]);
;   mx = xhalf_max(mx);
;   const float ms = (mx == NEG_INF) ? 0.f : mx;
;   if (__builtin_amdgcn_ballot_w64(mx > st.m) != 0ull) {
;     const float alpha = fexp2(st.m - ms);
;     st.l *= alpha;
; #pragma unroll
;     for (int vt = 0; vt < 4; ++vt)
; #pragma unroll
;       for (int i = 0; i < 16; ++i) st.o[vt][i] *= alpha;
;   }
;   st.m = mx;
;   float ps = 0.f;
; #pragma unroll
;   for (int i = 0; i < 16; ++i) { sc[i] = fexp2(sc[i] - ms); ps += sc[i]; }
;   st.l += ps;
;   bf16x8 pf[2]; pf[0] = pack8(sc); pf[1] = pack8(sc + 8);
;   pv_tile_lds(st.o, pf, stv, L);
; }
.LBB0_233:
	v_sub_f32_e32 v80, v80, v148
	v_exp_f32_e32 v80, v80
	v_sub_f32_e32 v81, v81, v148
	v_exp_f32_e32 v81, v81
	v_sub_f32_e32 v78, v78, v148
	v_exp_f32_e32 v78, v78
	v_sub_f32_e32 v79, v79, v148
	v_exp_f32_e32 v79, v79
	v_sub_f32_e32 v76, v76, v148
	v_add_f32_e32 v160, 0, v80
	v_exp_f32_e32 v76, v76
	v_sub_f32_e32 v77, v77, v148
	v_add_f32_e32 v160, v81, v160
	v_exp_f32_e32 v77, v77
	v_sub_f32_e32 v74, v74, v148
	v_add_f32_e32 v160, v78, v160
	v_exp_f32_e32 v74, v74
	v_sub_f32_e32 v75, v75, v148
	v_add_f32_e32 v160, v79, v160
	v_exp_f32_e32 v75, v75
	v_sub_f32_e32 v72, v72, v148
	v_add_f32_e32 v160, v76, v160
	v_exp_f32_e32 v161, v72
	v_add_f32_e32 v160, v77, v160
	v_add_f32_e32 v160, v74, v160
	v_add_f32_e32 v160, v75, v160
	v_sub_f32_e32 v73, v73, v148
	v_add_f32_e32 v72, v161, v160
	v_exp_f32_e32 v160, v73
	v_sub_f32_e32 v70, v70, v148
	v_exp_f32_e32 v162, v70
	v_sub_f32_e32 v71, v71, v148
	v_exp_f32_e32 v163, v71
	v_sub_f32_e32 v68, v68, v148
	v_exp_f32_e32 v68, v68
	v_sub_f32_e32 v69, v69, v148
	v_add_f32_e32 v72, v160, v72
	v_exp_f32_e32 v69, v69
	v_sub_f32_e32 v66, v66, v148
	v_add_f32_e32 v70, v162, v72
	v_exp_f32_e32 v164, v66
	v_sub_f32_e32 v67, v67, v148
	v_add_f32_e32 v70, v163, v70
	v_exp_f32_e32 v148, v67
	v_add_f32_e32 v70, v68, v70
	v_add_f32_e32 v70, v69, v70
	v_add_f32_e32 v66, v164, v70
	v_add_f32_e32 v66, v148, v66
	v_add_f32_e32 v0, v66, v0
	v_cvt_pk_bf16_f32 v66, v161, v160
	v_cvt_pk_bf16_f32 v72, v76, v77
	v_cvt_pk_bf16_f32 v73, v74, v75
	v_cvt_pk_bf16_f32 v70, v80, v81
	v_cvt_pk_bf16_f32 v71, v78, v79
	v_cvt_pk_bf16_f32 v67, v162, v163
	v_cvt_pk_bf16_f32 v68, v68, v69
	v_cvt_pk_bf16_f32 v69, v164, v148
	v_add_u32_e32 v190, s23, v181
	v_subrev_u32_e32 v240, s1, v185
	v_add_u32_e32 v240, v190, v240
	ds_read_b64 v[244:245], v240 offset:2048
	ds_read_b64 v[240:241], v240
	v_subrev_u32_e32 v242, s1, v182
	v_add_u32_e32 v242, v190, v242
	ds_read_b64 v[246:247], v242 offset:2048
	ds_read_b64 v[242:243], v242
	v_mov_b32_e32 v147, v146
	s_waitcnt lgkmcnt(4)
	v_mfma_f32_32x32x16_bf16 v[50:65], v[186:189], v[70:73], v[50:65]
	v_mfma_f32_32x32x16_bf16 v[50:65], v[194:197], v[66:69], v[50:65]
	v_mfma_f32_32x32x16_bf16 v[34:49], v[200:203], v[70:73], v[34:49]
	v_mfma_f32_32x32x16_bf16 v[34:49], v[228:231], v[66:69], v[34:49]
	v_mfma_f32_32x32x16_bf16 v[18:33], v[232:235], v[70:73], v[18:33]
	v_mfma_f32_32x32x16_bf16 v[2:17], v[236:239], v[70:73], v[2:17]
	s_waitcnt lgkmcnt(0)
	v_mfma_f32_32x32x16_bf16 v[18:33], v[240:243], v[66:69], v[18:33]
	v_mfma_f32_32x32x16_bf16 v[2:17], v[244:247], v[66:69], v[2:17]

; #define NEG_INF (-__builtin_inff())
; DI f32x16 mfma32(bf16x8 a, bf16x8 b, f32x16 c) { return __builtin_amdgcn_mfma_f32_32x32x16_bf16(a, b, c, 0, 0, 0); }
; DI f32x16 zero16() { f32x16 z; for (int i = 0; i < 16; ++i) z[i] = 0.f; return z; }
; #define LAS __attribute__((address_space(3)))
; DI f32x16 score_tile_lds(const bf16x8 (&qf)[8], const LAS unsigned char* st, const LaneKV& L) {
;   f32x16 acc = zero16();
; #pragma unroll
;   for (int ks = 0; ks < 8; ++ks) { const bf16x8 a = *(const LAS bf16x8*)(st + L.kx + (((unsigned)ks ^ L.xh) << 5)); acc = mfma32(a, qf[ks], acc); }
;   return acc;
; }
; DI void pv_tile_lds(f32x16 (&o)[4], const bf16x8 (&pf)[2], const LAS unsigned char* stv, const LaneKV& L) {
; #pragma unroll
;   for (int vt = 0; vt < 4; ++vt) {
; #pragma unroll
;     for (int s2 = 0; s2 < 2; ++s2) {
;       const s16x4 lo = *(const LAS s16x4*)(stv + vt * 2048 + L.vrow + L.vo[2 * s2]), hi = *(const LAS s16x4*)(stv + vt * 2048 + L.vrow + L.vo[2 * s2 + 1]);
;       const bf16x8 a = __builtin_shufflevector(lo, hi, 0, 1, 2, 3, 4, 5, 6, 7);
;       o[vt] = mfma32(a, pf[s2], o[vt]);
;     }
;   }
; }
; DI void nsa_winslc(const Params& p, const NsaCtx c) {
;     ...
;       if (kt >= mylo && kt <= myhi && t0 - (kt * 32 + 31) <= thr) {
;         const LAS unsigned char* sg = stg + (i % 3) * AT_STAGE;
;         f32x16 acc = score_tile_lds(qf, sg, L);
;         float sc[16];
;         const int key0 = kt * 32, d0 = tq - key0 - 4 * g;
;         const float fb = slope2 * (float)d0;
; #pragma unroll
;         for (int q = 0; q < 16; ++q) sc[q] = fmaf(slope2, (float)((q & 3) + 8 * (q >> 2)), acc[q]) - fb;
;         if (kt == mylo || kt == myhi) {
; #pragma unroll
;           for (int q = 0; q < 16; ++q) { const int dist = d0 - ((q & 3) + 8 * (q >> 2)); sc[q] = (dist >= 0 && dist < 512) ? sc[q] : NEG_INF; }
;         }
.LBB0_241:
	s_cmp_lt_i32 s1, s17
	s_cselect_b64 s[26:27], -1, 0
	s_cmp_gt_i32 s1, s16
	s_cselect_b64 s[28:29], -1, 0
	s_or_b64 s[26:27], s[26:27], s[28:29]
	s_and_b64 vcc, exec, s[26:27]
	s_cbranch_vccnz .LBB0_234
	s_cmp_gt_i32 s22, s10
	s_cbranch_scc1 .LBB0_234
	s_mul_hi_u32 s1, s24, 0xaaaaaaab
	s_lshr_b32 s1, s1, 1
	s_mul_i32 s1, s1, 0xc000
	v_add_u32_e32 v156, s23, v215
	v_subrev_u32_e32 v186, s1, v144
	v_add_u32_e32 v186, v156, v186
	ds_read_b128 v[186:189], v186
	v_subrev_u32_e32 v194, s1, v143
	v_add_u32_e32 v194, v156, v194
	ds_read_b128 v[194:197], v194
	v_subrev_u32_e32 v200, s1, v142
	v_add_u32_e32 v200, v156, v200
	ds_read_b128 v[200:203], v200
	v_subrev_u32_e32 v228, s1, v141
	v_add_u32_e32 v228, v156, v228
	ds_read_b128 v[228:231], v228
	v_subrev_u32_e32 v232, s1, v140
	v_add_u32_e32 v232, v156, v232
	ds_read_b128 v[232:235], v232
	v_subrev_u32_e32 v236, s1, v139
	v_add_u32_e32 v236, v156, v236
	ds_read_b128 v[236:239], v236
	v_subrev_u32_e32 v240, s1, v138
	v_add_u32_e32 v240, v156, v240
	ds_read_b128 v[240:243], v240
	v_subrev_u32_e32 v244, s1, v129
	v_add_u32_e32 v244, v156, v244
	ds_read_b128 v[244:247], v244
	s_cmp_lg_u32 s19, s24
	s_cselect_b64 s[26:27], -1, 0
	s_cmp_lg_u32 s18, s24
	s_cselect_b64 s[24:25], -1, 0
	s_and_b64 s[24:25], s[26:27], s[24:25]
	s_and_b64 vcc, exec, s[24:25]
	s_mov_b32 s24, 2.0
	s_mov_b32 s25, 0x40400000
	v_add_u32_e32 v148, s22, v145
	v_add_u32_e32 v146, 31, v148
	v_cvt_f32_i32_e32 v149, v146
	v_mul_f32_e32 v150, v114, v149
	s_waitcnt lgkmcnt(7)
	v_mfma_f32_32x32x16_bf16 v[66:81], v[186:189], v[82:85], 0
	s_waitcnt lgkmcnt(6)
	v_mfma_f32_32x32x16_bf16 v[66:81], v[194:197], v[86:89], v[66:81]
	s_waitcnt lgkmcnt(5)
	v_mfma_f32_32x32x16_bf16 v[66:81], v[200:203], v[90:93], v[66:81]
	s_waitcnt lgkmcnt(4)
	v_mfma_f32_32x32x16_bf16 v[66:81], v[228:231], v[94:97], v[66:81]
	s_waitcnt lgkmcnt(3)
	v_mfma_f32_32x32x16_bf16 v[66:81], v[232:235], v[98:101], v[66:81]
	s_waitcnt lgkmcnt(2)
	v_mfma_f32_32x32x16_bf16 v[66:81], v[236:239], v[102:105], v[66:81]
	s_waitcnt lgkmcnt(1)
	v_mfma_f32_32x32x16_bf16 v[66:81], v[240:243], v[106:109], v[66:81]
	s_waitcnt lgkmcnt(0)
	v_mfma_f32_32x32x16_bf16 v[66:81], v[244:247], v[110:113], v[66:81]
	v_add_u32_e32 v190, s23, v181
	v_subrev_u32_e32 v186, s1, v214
	v_add_u32_e32 v186, v190, v186
	ds_read_b64 v[186:187], v186
	v_subrev_u32_e32 v188, s1, v211
	v_add_u32_e32 v188, v190, v188
	ds_read_b64 v[188:189], v188
	v_subrev_u32_e32 v194, s1, v208
	v_add_u32_e32 v194, v190, v194
	ds_read_b64 v[194:195], v194
	v_subrev_u32_e32 v196, s1, v184
	v_add_u32_e32 v196, v190, v196
	ds_read_b64 v[196:197], v196
	v_subrev_u32_e32 v200, s1, v213
	v_add_u32_e32 v200, v190, v200
	ds_read_b64 v[200:201], v200
	v_subrev_u32_e32 v202, s1, v210
	v_add_u32_e32 v202, v190, v202
	ds_read_b64 v[202:203], v202
	v_subrev_u32_e32 v228, s1, v207
	v_add_u32_e32 v228, v190, v228
	ds_read_b64 v[228:229], v228
	v_subrev_u32_e32 v230, s1, v183
	v_add_u32_e32 v230, v190, v230
	ds_read_b64 v[230:231], v230
	v_subrev_u32_e32 v232, s1, v212
	v_add_u32_e32 v232, v190, v232
	ds_read_b64 v[236:237], v232 offset:2048
	ds_read_b64 v[232:233], v232
	v_subrev_u32_e32 v234, s1, v209
	v_add_u32_e32 v234, v190, v234
	ds_read_b64 v[238:239], v234 offset:2048
	ds_read_b64 v[234:235], v234
	v_pk_fma_f32 v[68:69], v[114:115], s[24:25], v[68:69]
	s_mov_b32 s24, 0x41000000
	s_mov_b32 s25, 0x41100000
	v_pk_fma_f32 v[70:71], v[114:115], s[24:25], v[70:71]
	s_mov_b32 s24, 0x41200000
	s_mov_b32 s25, 0x41300000
	v_pk_fma_f32 v[72:73], v[114:115], s[24:25], v[72:73]
	s_mov_b32 s24, 0x41800000
	s_mov_b32 s25, 0x41880000
	v_pk_fma_f32 v[152:153], v[114:115], s[24:25], v[74:75]
	s_mov_b32 s24, 0x41900000
	s_mov_b32 s25, 0x41980000
	v_pk_fma_f32 v[154:155], v[114:115], s[24:25], v[76:77]
	s_mov_b32 s24, 0x41c00000
	s_mov_b32 s25, 0x41c80000
	v_pk_fma_f32 v[156:157], v[114:115], s[24:25], v[78:79]
	s_mov_b32 s24, 0x41d00000
	s_mov_b32 s25, 0x41d80000
	v_fma_f32 v66, 0, v114, v66
	v_add_f32_e32 v67, v114, v67
	v_pk_fma_f32 v[158:159], v[114:115], s[24:25], v[80:81]
	v_pk_add_f32 v[80:81], v[66:67], v[150:151] op_sel_hi:[1,0] neg_lo:[0,1] neg_hi:[0,1]
	v_pk_add_f32 v[78:79], v[68:69], v[150:151] op_sel_hi:[1,0] neg_lo:[0,1] neg_hi:[0,1]
	v_pk_add_f32 v[76:77], v[70:71], v[150:151] op_sel_hi:[1,0] neg_lo:[0,1] neg_hi:[0,1]
	v_pk_add_f32 v[74:75], v[72:73], v[150:151] op_sel_hi:[1,0] neg_lo:[0,1] neg_hi:[0,1]
	v_pk_add_f32 v[72:73], v[152:153], v[150:151] op_sel_hi:[1,0] neg_lo:[0,1] neg_hi:[0,1]
	v_pk_add_f32 v[70:71], v[154:155], v[150:151] op_sel_hi:[1,0] neg_lo:[0,1] neg_hi:[0,1]
	v_pk_add_f32 v[68:69], v[156:157], v[150:151] op_sel_hi:[1,0] neg_lo:[0,1] neg_hi:[0,1]
	v_pk_add_f32 v[66:67], v[158:159], v[150:151] op_sel_hi:[1,0] neg_lo:[0,1] neg_hi:[0,1]
	s_cbranch_vccnz .LBB0_245
	s_movk_i32 s24, 0x200
	v_add_u32_e32 v148, 30, v148
	v_cmp_gt_u32_e32 vcc, s24, v146
	v_add_u32_e32 v149, -2, v146
	s_nop 0
	v_cndmask_b32_e32 v80, v248, v80, vcc
	v_cmp_gt_u32_e32 vcc, s24, v148
	v_add_u32_e32 v148, -3, v146
	s_nop 0
	v_cndmask_b32_e32 v81, v248, v81, vcc
	v_cmp_gt_u32_e32 vcc, s24, v148
	v_add_u32_e32 v148, -9, v146
	s_nop 0
	v_cndmask_b32_e32 v79, v248, v79, vcc
	v_cmp_gt_u32_e32 vcc, s24, v149
	v_add_u32_e32 v149, -8, v146
	s_nop 0
	v_cndmask_b32_e32 v78, v248, v78, vcc
	v_cmp_gt_u32_e32 vcc, s24, v148
	v_add_u32_e32 v148, -11, v146
	s_nop 0
	v_cndmask_b32_e32 v77, v248, v77, vcc
	v_cmp_gt_u32_e32 vcc, s24, v149
	v_add_u32_e32 v149, -10, v146
	s_nop 0
	v_cndmask_b32_e32 v76, v248, v76, vcc
	v_cmp_gt_u32_e32 vcc, s24, v148
	v_add_u32_e32 v148, -16, v146
	s_nop 0
	v_cndmask_b32_e32 v75, v248, v75, vcc
	v_cmp_gt_u32_e32 vcc, s24, v149
	v_subrev_u32_e32 v149, 17, v146
	s_nop 0
	v_cndmask_b32_e32 v74, v248, v74, vcc
	v_cmp_gt_u32_e32 vcc, s24, v149
	v_subrev_u32_e32 v149, 18, v146
	s_nop 0
	v_cndmask_b32_e32 v73, v248, v73, vcc
	v_cmp_gt_u32_e32 vcc, s24, v148
	v_subrev_u32_e32 v148, 19, v146
	s_nop 0
	v_cndmask_b32_e32 v72, v248, v72, vcc
	v_cmp_gt_u32_e32 vcc, s24, v148
	v_subrev_u32_e32 v148, 25, v146
	s_nop 0
	v_cndmask_b32_e32 v71, v248, v71, vcc
	v_cmp_gt_u32_e32 vcc, s24, v149
	v_subrev_u32_e32 v149, 24, v146
	s_nop 0
	v_cndmask_b32_e32 v70, v248, v70, vcc
	v_cmp_gt_u32_e32 vcc, s24, v148
	v_subrev_u32_e32 v148, 27, v146
	v_subrev_u32_e32 v146, 26, v146
	v_cndmask_b32_e32 v69, v248, v69, vcc
	v_cmp_gt_u32_e32 vcc, s24, v149
	s_nop 1
	v_cndmask_b32_e32 v68, v248, v68, vcc
	v_cmp_gt_u32_e32 vcc, s24, v148
	s_nop 1
	v_cndmask_b32_e32 v67, v248, v67, vcc
	v_cmp_gt_u32_e32 vcc, s24, v146
	s_nop 1
	v_cndmask_b32_e32 v66, v248, v66, vcc

; #define NEG_INF (-__builtin_inff())
; DI f32x16 mfma32(bf16x8 a, bf16x8 b, f32x16 c) { return __builtin_amdgcn_mfma_f32_32x32x16_bf16(a, b, c, 0, 0, 0); }
; DI f32x16 zero16() { f32x16 z; for (int i = 0; i < 16; ++i) z[i] = 0.f; return z; }
; #define LAS __attribute__((address_space(3)))
; DI f32x16 score_tile_lds(const bf16x8 (&qf)[8], const LAS unsigned char* st, const LaneKV& L) {
;   f32x16 acc = zero16();
; #pragma unroll
;   for (int ks = 0; ks < 8; ++ks) { const bf16x8 a = *(const LAS bf16x8*)(st + L.kx + (((unsigned)ks ^ L.xh) << 5)); acc = mfma32(a, qf[ks], acc); }
;   return acc;
; }
; DI void pv_tile_lds(f32x16 (&o)[4], const bf16x8 (&pf)[2], const LAS unsigned char* stv, const LaneKV& L) {
; #pragma unroll
;   for (int vt = 0; vt < 4; ++vt) {
; #pragma unroll
;     for (int s2 = 0; s2 < 2; ++s2) {
;       const s16x4 lo = *(const LAS s16x4*)(stv + vt * 2048 + L.vrow + L.vo[2 * s2]), hi = *(const LAS s16x4*)(stv + vt * 2048 + L.vrow + L.vo[2 * s2 + 1]);
;       const bf16x8 a = __builtin_shufflevector(lo, hi, 0, 1, 2, 3, 4, 5, 6, 7);
;       o[vt] = mfma32(a, pf[s2], o[vt]);
;     }
;   }
; }
; DI void nsa_winslc(const Params& p, const NsaCtx c) {
;     ...
;       const int mb = kt >> 1, key0 = kt * 32;
;       if (((uni >> mb) & 1ull) && key0 <= t0 + 31 && t0 - (key0 + 31) <= thr) {
;         const bool mine = (mymask >> mb) & 1ull;
;         const LAS unsigned char* sg = stg + (i % 3) * AT_STAGE;
;         f32x16 acc = score_tile_lds(qf, sg, L);
;         float sc[16];
;         const int d0 = tq - key0 - 4 * g;
;         const float fb = mine ? slope2 * (float)d0 : __builtin_inff();
; #pragma unroll
;         for (int q = 0; q < 16; ++q) sc[q] = fmaf(slope2, (float)((q & 3) + 8 * (q >> 2)), acc[q]) - fb;
;         if (key0 >= t0) {
; #pragma unroll
;           for (int q = 0; q < 16; ++q) sc[q] = (d0 - ((q & 3) + 8 * (q >> 2)) >= 0) ? sc[q] : NEG_INF;
;         }
.LBB0_269:
	s_ashr_i32 s2, s17, 1
	s_lshl_b64 s[2:3], 1, s2
	s_lshl_b32 s17, s17, 5
	s_and_b64 s[18:19], s[2:3], s[0:1]
	s_cmp_eq_u64 s[18:19], 0
	s_cselect_b64 s[18:19], -1, 0
	s_cmp_gt_i32 s17, s4
	s_cselect_b64 s[20:21], -1, 0
	s_sub_i32 s22, s5, s17
	s_cmp_gt_i32 s22, s10
	s_cselect_b64 s[22:23], -1, 0
	s_or_b64 s[20:21], s[20:21], s[22:23]
	s_or_b64 s[18:19], s[20:21], s[18:19]
	s_and_b64 vcc, exec, s[18:19]
	s_cbranch_vccnz .LBB0_275
	s_mul_hi_u32 s15, s15, 0xaaaaaaab
	s_lshr_b32 s15, s15, 1
	s_mul_i32 s15, s15, 0xc000
	v_add_u32_e32 v121, s7, v215
	v_subrev_u32_e32 v186, s15, v223
	v_add_u32_e32 v186, v121, v186
	ds_read_b128 v[186:189], v186
	v_subrev_u32_e32 v194, s15, v222
	v_add_u32_e32 v194, v121, v194
	ds_read_b128 v[194:197], v194
	v_subrev_u32_e32 v200, s15, v221
	v_add_u32_e32 v200, v121, v200
	ds_read_b128 v[200:203], v200
	v_subrev_u32_e32 v228, s15, v220
	v_add_u32_e32 v228, v121, v228
	ds_read_b128 v[228:231], v228
	v_subrev_u32_e32 v232, s15, v219
	v_add_u32_e32 v232, v121, v232
	ds_read_b128 v[232:235], v232
	v_subrev_u32_e32 v236, s15, v218
	v_add_u32_e32 v236, v121, v236
	ds_read_b128 v[236:239], v236
	v_subrev_u32_e32 v240, s15, v217
	v_add_u32_e32 v240, v121, v240
	ds_read_b128 v[240:243], v240
	v_subrev_u32_e32 v244, s15, v117
	v_add_u32_e32 v244, v121, v244
	ds_read_b128 v[244:247], v244
	s_cmp_lt_i32 s17, s9
	v_or_b32_e32 v120, s17, v180
	v_sub_u32_e32 v120, v116, v120
	v_cvt_f32_i32_e32 v121, v120
	v_mul_f32_e32 v121, v114, v121
	v_and_b32_e32 v131, s3, v119
	v_and_b32_e32 v130, s2, v118
	s_mov_b32 s2, 2.0
	s_mov_b32 s3, 0x40400000
	v_cmp_ne_u64_e32 vcc, 0, v[130:131]
	v_mov_b32_e32 v130, 0x7f800000
	s_waitcnt lgkmcnt(7)
	v_mfma_f32_32x32x16_bf16 v[66:81], v[186:189], v[82:85], 0
	s_waitcnt lgkmcnt(6)
	v_mfma_f32_32x32x16_bf16 v[66:81], v[194:197], v[86:89], v[66:81]
	s_waitcnt lgkmcnt(5)
	v_mfma_f32_32x32x16_bf16 v[66:81], v[200:203], v[90:93], v[66:81]
	s_waitcnt lgkmcnt(4)
	v_mfma_f32_32x32x16_bf16 v[66:81], v[228:231], v[94:97], v[66:81]
	s_waitcnt lgkmcnt(3)
	v_mfma_f32_32x32x16_bf16 v[66:81], v[232:235], v[98:101], v[66:81]
	s_waitcnt lgkmcnt(2)
	v_mfma_f32_32x32x16_bf16 v[66:81], v[236:239], v[102:105], v[66:81]
	s_waitcnt lgkmcnt(1)
	v_mfma_f32_32x32x16_bf16 v[66:81], v[240:243], v[106:109], v[66:81]
	s_waitcnt lgkmcnt(0)
	v_mfma_f32_32x32x16_bf16 v[66:81], v[244:247], v[110:113], v[66:81]
	v_cndmask_b32_e32 v130, v130, v121, vcc
	v_add_u32_e32 v190, s7, v181
	v_subrev_u32_e32 v186, s15, v214
	v_add_u32_e32 v186, v190, v186
	ds_read_b64 v[186:187], v186
	v_subrev_u32_e32 v188, s15, v211
	v_add_u32_e32 v188, v190, v188
	ds_read_b64 v[188:189], v188
	v_subrev_u32_e32 v194, s15, v213
	v_add_u32_e32 v194, v190, v194
	ds_read_b64 v[194:195], v194
	v_subrev_u32_e32 v196, s15, v210
	v_add_u32_e32 v196, v190, v196
	ds_read_b64 v[196:197], v196
	v_subrev_u32_e32 v200, s15, v208
	v_add_u32_e32 v200, v190, v200
	ds_read_b64 v[200:201], v200
	v_subrev_u32_e32 v202, s15, v184
	v_add_u32_e32 v202, v190, v202
	ds_read_b64 v[202:203], v202
	v_subrev_u32_e32 v228, s15, v207
	v_add_u32_e32 v228, v190, v228
	ds_read_b64 v[228:229], v228
	v_subrev_u32_e32 v230, s15, v183
	v_add_u32_e32 v230, v190, v230
	ds_read_b64 v[230:231], v230
	v_subrev_u32_e32 v232, s15, v212
	v_add_u32_e32 v232, v190, v232
	ds_read_b64 v[236:237], v232 offset:2048
	ds_read_b64 v[232:233], v232
	v_subrev_u32_e32 v234, s15, v209
	v_add_u32_e32 v234, v190, v234
	ds_read_b64 v[238:239], v234 offset:2048
	ds_read_b64 v[234:235], v234
	v_pk_fma_f32 v[68:69], v[114:115], s[2:3], v[68:69]
	s_mov_b32 s2, 0x41000000
	s_mov_b32 s3, 0x41100000
	v_pk_fma_f32 v[70:71], v[114:115], s[2:3], v[70:71]
	s_mov_b32 s2, 0x41200000
	s_mov_b32 s3, 0x41300000
	v_pk_fma_f32 v[72:73], v[114:115], s[2:3], v[72:73]
	s_mov_b32 s2, 0x41800000
	s_mov_b32 s3, 0x41880000
	v_pk_fma_f32 v[132:133], v[114:115], s[2:3], v[74:75]
	s_mov_b32 s2, 0x41900000
	s_mov_b32 s3, 0x41980000
	v_pk_fma_f32 v[134:135], v[114:115], s[2:3], v[76:77]
	s_mov_b32 s2, 0x41c00000
	s_mov_b32 s3, 0x41c80000
	v_pk_fma_f32 v[136:137], v[114:115], s[2:3], v[78:79]
	s_mov_b32 s2, 0x41d00000
	s_mov_b32 s3, 0x41d80000
	v_fma_f32 v66, 0, v114, v66
	v_add_f32_e32 v67, v114, v67
	v_pk_fma_f32 v[138:139], v[114:115], s[2:3], v[80:81]
	v_pk_add_f32 v[80:81], v[66:67], v[130:131] op_sel_hi:[1,0] neg_lo:[0,1] neg_hi:[0,1]
	v_pk_add_f32 v[78:79], v[68:69], v[130:131] op_sel_hi:[1,0] neg_lo:[0,1] neg_hi:[0,1]
	v_pk_add_f32 v[76:77], v[70:71], v[130:131] op_sel_hi:[1,0] neg_lo:[0,1] neg_hi:[0,1]
	v_pk_add_f32 v[74:75], v[72:73], v[130:131] op_sel_hi:[1,0] neg_lo:[0,1] neg_hi:[0,1]
	v_pk_add_f32 v[72:73], v[132:133], v[130:131] op_sel_hi:[1,0] neg_lo:[0,1] neg_hi:[0,1]
	v_pk_add_f32 v[70:71], v[134:135], v[130:131] op_sel_hi:[1,0] neg_lo:[0,1] neg_hi:[0,1]
	v_pk_add_f32 v[68:69], v[136:137], v[130:131] op_sel_hi:[1,0] neg_lo:[0,1] neg_hi:[0,1]
	v_pk_add_f32 v[66:67], v[138:139], v[130:131] op_sel_hi:[1,0] neg_lo:[0,1] neg_hi:[0,1]
	s_cbranch_scc1 .LBB0_272
	v_cmp_lt_i32_e32 vcc, 0, v120
	s_nop 1
	v_cndmask_b32_e32 v81, v248, v81, vcc
	v_cmp_lt_i32_e32 vcc, -1, v120
	s_nop 1
	v_cndmask_b32_e32 v80, v248, v80, vcc
	v_cmp_lt_i32_e32 vcc, 2, v120
	s_nop 1
	v_cndmask_b32_e32 v79, v248, v79, vcc
	v_cmp_lt_i32_e32 vcc, 1, v120
	s_nop 1
	v_cndmask_b32_e32 v78, v248, v78, vcc
	v_cmp_lt_i32_e32 vcc, 8, v120
	s_nop 1
	v_cndmask_b32_e32 v77, v248, v77, vcc
	v_cmp_lt_i32_e32 vcc, 7, v120
	s_nop 1
	v_cndmask_b32_e32 v76, v248, v76, vcc
	v_cmp_lt_i32_e32 vcc, 10, v120
	s_nop 1
	v_cndmask_b32_e32 v75, v248, v75, vcc
	v_cmp_lt_i32_e32 vcc, 9, v120
	s_nop 1
	v_cndmask_b32_e32 v74, v248, v74, vcc
	v_cmp_lt_i32_e32 vcc, 16, v120
	s_nop 1
	v_cndmask_b32_e32 v73, v248, v73, vcc
	v_cmp_lt_i32_e32 vcc, 15, v120
	s_nop 1
	v_cndmask_b32_e32 v72, v248, v72, vcc
	v_cmp_lt_i32_e32 vcc, 18, v120
	s_nop 1
	v_cndmask_b32_e32 v71, v248, v71, vcc
	v_cmp_lt_i32_e32 vcc, 17, v120
	s_nop 1
	v_cndmask_b32_e32 v70, v248, v70, vcc
	v_cmp_lt_i32_e32 vcc, 24, v120
	s_nop 1
	v_cndmask_b32_e32 v69, v248, v69, vcc
	v_cmp_lt_i32_e32 vcc, 23, v120
	s_nop 1
	v_cndmask_b32_e32 v68, v248, v68, vcc
	v_cmp_lt_i32_e32 vcc, 26, v120
	s_nop 1
	v_cndmask_b32_e32 v67, v248, v67, vcc
	v_cmp_lt_i32_e32 vcc, 25, v120
	s_nop 1
	v_cndmask_b32_e32 v66, v248, v66, vcc

; #define NEG_INF (-__builtin_inff())
; DI float xhalf_max(float v) { const auto r = __builtin_amdgcn_permlane32_swap(__float_as_uint(v), __float_as_uint(v), false, false); return fmaxf(__uint_as_float(r[0]), __uint_as_float(r[1])); }
; DI float fexp2(float x) { return __builtin_amdgcn_exp2f(x); }
; DI f32x16 mfma32(bf16x8 a, bf16x8 b, f32x16 c) { return __builtin_amdgcn_mfma_f32_32x32x16_bf16(a, b, c, 0, 0, 0); }
; #define LAS __attribute__((address_space(3)))
; DI bf16x8 pack8(const float* p) { u32x4 o; o.x = pk2h(p[0], p[1]); o.y = pk2h(p[2], p[3]); o.z = pk2h(p[4], p[5]); o.w = pk2h(p[6], p[7]); return __builtin_bit_cast(bf16x8, o); }
; DI void pv_tile_lds(f32x16 (&o)[4], const bf16x8 (&pf)[2], const LAS unsigned char* stv, const LaneKV& L) {
; #pragma unroll
;   for (int vt = 0; vt < 4; ++vt) {
; #pragma unroll
;     for (int s2 = 0; s2 < 2; ++s2) {
;       const s16x4 lo = *(const LAS s16x4*)(stv + vt * 2048 + L.vrow + L.vo[2 * s2]), hi = *(const LAS s16x4*)(stv + vt * 2048 + L.vrow + L.vo[2 * s2 + 1]);
;       const bf16x8 a = __builtin_shufflevector(lo, hi, 0, 1, 2, 3, 4, 5, 6, 7);
;       o[vt] = mfma32(a, pf[s2], o[vt]);
;     }
;   }
; }
; DI void softmax_step_lds(AttnState& st, float (&sc)[16], const LAS unsigned char* stv, const LaneKV& L) {
;   float mx = st.m;
; #pragma unroll
;   for (int i = 0; i < 16; ++i) mx = fmaxf(mx, sc[i]);
;   mx = xhalf_max(mx);
;   const float ms = (mx == NEG_INF) ? 0.f : mx;
;   if (__builtin_amdgcn_ballot_w64(mx > st.m) != 0ull) {
;     const float alpha = fexp2(st.m - ms);
;     st.l *= alpha;
; #pragma unroll
;     for (int vt = 0; vt < 4; ++vt)
; #pragma unroll
;       for (int i = 0; i < 16; ++i) st.o[vt][i] *= alpha;
;   }
;   st.m = mx;
;   float ps = 0.f;
; #pragma unroll
;   for (int i = 0; i < 16; ++i) { sc[i] = fexp2(sc[i] - ms); ps += sc[i]; }
;   st.l += ps;
;   bf16x8 pf[2]; pf[0] = pack8(sc); pf[1] = pack8(sc + 8);
;   pv_tile_lds(st.o, pf, stv, L);
; }
.LBB0_274:
	v_sub_f32_e32 v80, v80, v120
	v_sub_f32_e32 v78, v78, v120
	v_sub_f32_e32 v76, v76, v120
	v_sub_f32_e32 v74, v74, v120
	v_sub_f32_e32 v72, v72, v120
	v_sub_f32_e32 v70, v70, v120
	v_sub_f32_e32 v68, v68, v120
	v_sub_f32_e32 v66, v66, v120
	v_exp_f32_e32 v137, v80
	v_sub_f32_e32 v80, v81, v120
	v_exp_f32_e32 v142, v78
	v_sub_f32_e32 v78, v79, v120
	v_exp_f32_e32 v144, v76
	v_sub_f32_e32 v76, v77, v120
	v_exp_f32_e32 v146, v74
	v_sub_f32_e32 v74, v75, v120
	v_exp_f32_e32 v148, v72
	v_sub_f32_e32 v72, v73, v120
	v_exp_f32_e32 v150, v70
	v_sub_f32_e32 v70, v71, v120
	v_exp_f32_e32 v152, v68
	v_sub_f32_e32 v68, v69, v120
	v_exp_f32_e32 v154, v66
	v_sub_f32_e32 v66, v67, v120
	v_exp_f32_e32 v138, v80
	v_exp_f32_e32 v143, v78
	v_exp_f32_e32 v145, v76
	v_exp_f32_e32 v147, v74
	v_exp_f32_e32 v149, v72
	v_exp_f32_e32 v151, v70
	v_exp_f32_e32 v153, v68
	v_exp_f32_e32 v120, v66
	v_cvt_pk_bf16_f32 v66, v137, v138
	v_cvt_pk_bf16_f32 v67, v142, v143
	v_cvt_pk_bf16_f32 v68, v144, v145
	v_cvt_pk_bf16_f32 v69, v146, v147
	v_add_u32_e32 v190, s7, v181
	v_subrev_u32_e32 v240, s15, v185
	v_add_u32_e32 v240, v190, v240
	ds_read_b64 v[244:245], v240 offset:2048
	ds_read_b64 v[240:241], v240
	v_subrev_u32_e32 v242, s15, v182
	v_add_u32_e32 v242, v190, v242
	ds_read_b64 v[246:247], v242 offset:2048
	ds_read_b64 v[242:243], v242
	s_waitcnt lgkmcnt(4)
	v_mfma_f32_32x32x16_bf16 v[2:17], v[186:189], v[66:69], v[2:17]
	v_cvt_pk_bf16_f32 v74, v148, v149
	v_cvt_pk_bf16_f32 v75, v150, v151
	v_cvt_pk_bf16_f32 v76, v152, v153
	v_cvt_pk_bf16_f32 v77, v154, v120
	v_mfma_f32_32x32x16_bf16 v[18:33], v[194:197], v[66:69], v[18:33]
	v_add_f32_e32 v135, 0, v137
	v_mfma_f32_32x32x16_bf16 v[2:17], v[200:203], v[74:77], v[2:17]
	v_mfma_f32_32x32x16_bf16 v[18:33], v[228:231], v[74:77], v[18:33]
	v_add_f32_e32 v155, v138, v135
	v_mfma_f32_32x32x16_bf16 v[34:49], v[232:235], v[66:69], v[34:49]
	v_add_f32_e32 v70, v142, v155
	v_add_f32_e32 v70, v143, v70
	v_mfma_f32_32x32x16_bf16 v[50:65], v[236:239], v[66:69], v[50:65]
	v_add_f32_e32 v70, v144, v70
	v_add_f32_e32 v70, v145, v70
	v_add_f32_e32 v70, v146, v70
	v_add_f32_e32 v70, v147, v70
	v_add_f32_e32 v70, v148, v70
	v_add_f32_e32 v70, v149, v70
	s_waitcnt lgkmcnt(0)
	v_mfma_f32_32x32x16_bf16 v[34:49], v[240:243], v[74:77], v[34:49]
	v_add_f32_e32 v70, v150, v70
	v_add_f32_e32 v70, v151, v70
	v_add_f32_e32 v66, v152, v70
	v_add_f32_e32 v66, v153, v66
	v_add_f32_e32 v66, v154, v66
	v_add_f32_e32 v66, v120, v66
	v_add_f32_e32 v0, v66, v0
	v_mfma_f32_32x32x16_bf16 v[50:65], v[244:247], v[74:77], v[50:65]
	s_branch .LBB0_276

; #define NEG_INF (-__builtin_inff())
; #define LAS __attribute__((address_space(3)))
; #define AT_WAIT_V(n) asm volatile("s_waitcnt vmcnt(" #n ")" ::: "memory")
; #define AT_BAR() __builtin_amdgcn_s_barrier()
; DI void nsa_winslc(const Params& p, const NsaCtx c) {
;     ...
; #pragma unroll 1
;     for (int i = 0; i < nsteps; ++i) {
;       const int kt = __builtin_amdgcn_readfirstlane(tl[i]);
;       if (i + 1 < nsteps) AT_WAIT_V(2); else AT_WAIT_V(0);
;       AT_BAR();
;       if (i + 2 < nsteps) { const int k2 = __builtin_amdgcn_readfirstlane(tl[i + 2]); kv_issue(stg + ((i + 2) % 3) * AT_STAGE, KS + (size_t)k2 * 4096, VST + (size_t)k2 * 4096, L); }
;       const int mb = kt >> 1, key0 = kt * 32;
;       if (((uni >> mb) & 1ull) && key0 <= t0 + 31 && t0 - (key0 + 31) <= thr) {
;         const bool mine = (mymask >> mb) & 1ull;
;         const LAS unsigned char* sg = stg + (i % 3) * AT_STAGE;
;         f32x16 acc = score_tile_lds(qf, sg, L);
;         float sc[16];
;         const int d0 = tq - key0 - 4 * g;
;         const float fb = mine ? slope2 * (float)d0 : __builtin_inff();
; #pragma unroll
;         for (int q = 0; q < 16; ++q) sc[q] = fmaf(slope2, (float)((q & 3) + 8 * (q >> 2)), acc[q]) - fb;
;         if (key0 >= t0) {
; #pragma unroll
;           for (int q = 0; q < 16; ++q) sc[q] = (d0 - ((q & 3) + 8 * (q >> 2)) >= 0) ? sc[q] : NEG_INF;
;         }
;         softmax_step_lds(st, sc, sg + 8192, L);
;       }
;     }
.Lsel_exit:
	v_mov_b32_e32 v145, v17
	v_mov_b32_e32 v144, v16
	v_mov_b32_e32 v147, v15
	v_mov_b32_e32 v146, v14
	v_mov_b32_e32 v149, v13
	v_mov_b32_e32 v148, v12
	v_mov_b32_e32 v151, v11
	v_mov_b32_e32 v150, v10
	v_mov_b32_e32 v153, v9
	v_mov_b32_e32 v152, v8
	v_mov_b32_e32 v155, v7
	v_mov_b32_e32 v154, v6
	v_mov_b32_e32 v157, v5
	v_mov_b32_e32 v156, v4
	v_mov_b32_e32 v161, v3
	v_mov_b32_e32 v160, v2
	v_mov_b32_e32 v139, v33
	v_mov_b32_e32 v138, v32
	v_mov_b32_e32 v163, v31
	v_mov_b32_e32 v162, v30
	v_mov_b32_e32 v165, v29
	v_mov_b32_e32 v164, v28
	v_mov_b32_e32 v167, v27
	v_mov_b32_e32 v166, v26
	v_mov_b32_e32 v169, v25
	v_mov_b32_e32 v168, v24
	v_mov_b32_e32 v171, v23
	v_mov_b32_e32 v170, v22
	v_mov_b32_e32 v173, v21
	v_mov_b32_e32 v172, v20
	v_mov_b32_e32 v175, v19
	v_mov_b32_e32 v174, v18
	v_mov_b32_e32 v77, v49
	v_mov_b32_e32 v76, v48
	v_mov_b32_e32 v121, v47
	v_mov_b32_e32 v120, v46
	v_mov_b32_e32 v133, v45
	v_mov_b32_e32 v132, v44
	v_mov_b32_e32 v135, v43
	v_mov_b32_e32 v134, v42
	v_mov_b32_e32 v137, v41
	v_mov_b32_e32 v136, v40
	v_mov_b32_e32 v141, v39
	v_mov_b32_e32 v140, v38
	v_mov_b32_e32 v143, v37
	v_mov_b32_e32 v142, v36
	v_mov_b32_e32 v159, v35
	v_mov_b32_e32 v158, v34
	v_mov_b32_e32 v67, v65
	v_mov_b32_e32 v66, v64
	v_mov_b32_e32 v69, v63
	v_mov_b32_e32 v68, v62
	v_mov_b32_e32 v71, v61
	v_mov_b32_e32 v70, v60
	v_mov_b32_e32 v73, v59
	v_mov_b32_e32 v72, v58
	v_mov_b32_e32 v75, v57
	v_mov_b32_e32 v74, v56
	v_mov_b32_e32 v79, v55
	v_mov_b32_e32 v78, v54
	v_mov_b32_e32 v81, v53
	v_mov_b32_e32 v80, v52
	v_mov_b32_e32 v131, v51
	v_mov_b32_e32 v130, v50
	s_branch .LBB0_199
